# v15 + MLP-out residual epilogue: residual-row loads double-buffered one row group ahead, counted waits instead of full drains
# baseline (speedup 1.0000x reference)
.LBB0_1511:
	s_lshl_b32 s4, s17, 8
	s_ashr_i32 s17, s21, 2
	s_andn2_b32 s17, s17, 63
	v_and_b32_e32 v188, 15, v186
	s_add_i32 s21, s17, s4
	v_or_b32_e32 v174, s21, v188
	v_ashrrev_i32_e32 v175, 31, v174
	v_lshlrev_b64 v[146:147], 11, v[174:175]
	v_lshl_add_u64 v[178:179], v[146:147], 0, v[162:163]
	v_lshl_add_u64 v[180:181], v[178:179], 1, s[50:51]
	global_load_dwordx4 v[234:237], v[180:181], off
	global_load_dwordx4 v[238:241], v[180:181], off offset:256
	v_add_co_u32_e32 v208, vcc, 0x10000, v180
	s_nop 1
	v_addc_co_u32_e32 v209, vcc, 0, v181, vcc
	global_load_dwordx4 v[242:245], v[208:209], off
	s_nop 0
	global_load_dwordx4 v[246:249], v[208:209], off offset:256
	s_mov_b64 s[26:27], -1
	s_and_b64 vcc, exec, s[94:95]
	s_waitcnt vmcnt(2)
	v_lshlrev_b32_e32 v176, 16, v234
	v_and_b32_e32 v177, 0xffff0000, v234
	v_lshlrev_b32_e32 v150, 16, v235
	v_and_b32_e32 v151, 0xffff0000, v235
	v_lshlrev_b32_e32 v182, 16, v236
	v_and_b32_e32 v183, 0xffff0000, v236
	v_lshlrev_b32_e32 v152, 16, v237
	v_and_b32_e32 v153, 0xffff0000, v237
	v_pk_fma_f32 v[144:145], v[144:145], v[64:65], v[150:151]
	v_pk_fma_f32 v[142:143], v[142:143], v[62:63], v[176:177]
	v_pk_fma_f32 v[140:141], v[140:141], v[60:61], v[152:153]
	v_pk_fma_f32 v[138:139], v[138:139], v[58:59], v[182:183]
	s_cbranch_vccz .LBB0_1513
	v_cvt_pk_bf16_f32 v150, v142, v143
	v_cvt_pk_bf16_f32 v151, v144, v145
	v_cvt_pk_bf16_f32 v152, v138, v139
	v_cvt_pk_bf16_f32 v153, v140, v141
	s_mov_b64 s[26:27], 0

.LBB0_1517:
	v_lshlrev_b32_e32 v138, 16, v238
	v_and_b32_e32 v139, 0xffff0000, v238
	v_lshlrev_b32_e32 v140, 16, v239
	v_and_b32_e32 v141, 0xffff0000, v239
	v_lshlrev_b32_e32 v142, 16, v240
	v_and_b32_e32 v143, 0xffff0000, v240
	v_lshlrev_b32_e32 v144, 16, v241
	v_and_b32_e32 v145, 0xffff0000, v241
	v_pk_fma_f32 v[136:137], v[136:137], v[56:57], v[140:141]
	v_pk_fma_f32 v[134:135], v[134:135], v[54:55], v[138:139]
	v_pk_fma_f32 v[132:133], v[132:133], v[52:53], v[144:145]
	v_pk_fma_f32 v[130:131], v[130:131], v[50:51], v[142:143]
	s_mov_b64 s[26:27], -1
	s_and_b64 vcc, exec, s[94:95]
	s_cbranch_vccz .LBB0_1519
	v_cvt_pk_bf16_f32 v138, v134, v135
	v_cvt_pk_bf16_f32 v139, v136, v137
	v_cvt_pk_bf16_f32 v140, v130, v131
	v_cvt_pk_bf16_f32 v141, v132, v133
	global_store_dwordx4 v[178:179], v[138:141], off offset:256
	s_mov_b64 s[26:27], 0

.LBB0_1525:
	v_add_co_u32_e32 v208, vcc, 0x20000, v180
	s_mov_b64 s[26:27], -1
	s_waitcnt lgkmcnt(0)
	v_addc_co_u32_e32 v209, vcc, 0, v181, vcc
	global_load_dwordx4 v[234:237], v[208:209], off
	s_nop 0
	global_load_dwordx4 v[238:241], v[208:209], off offset:256
	s_and_b64 vcc, exec, s[94:95]
	s_waitcnt vmcnt(5)
	v_lshlrev_b32_e32 v140, 16, v242
	v_and_b32_e32 v141, 0xffff0000, v242
	v_lshlrev_b32_e32 v134, 16, v243
	v_and_b32_e32 v135, 0xffff0000, v243
	v_lshlrev_b32_e32 v142, 16, v244
	v_and_b32_e32 v143, 0xffff0000, v244
	v_lshlrev_b32_e32 v136, 16, v245
	v_and_b32_e32 v137, 0xffff0000, v245
	v_pk_fma_f32 v[128:129], v[128:129], v[64:65], v[134:135]
	v_pk_fma_f32 v[126:127], v[126:127], v[62:63], v[140:141]
	v_pk_fma_f32 v[124:125], v[124:125], v[60:61], v[136:137]
	v_pk_fma_f32 v[122:123], v[122:123], v[58:59], v[142:143]
	s_cbranch_vccz .LBB0_1527
	v_add_co_u32_e32 v140, vcc, 0x10000, v178
	v_cvt_pk_bf16_f32 v134, v126, v127
	v_cvt_pk_bf16_f32 v135, v128, v129
	v_cvt_pk_bf16_f32 v136, v122, v123
	v_cvt_pk_bf16_f32 v137, v124, v125
	s_nop 1
	v_addc_co_u32_e32 v141, vcc, 0, v179, vcc
	global_store_dwordx4 v[140:141], v[134:137], off
	s_mov_b64 s[26:27], 0

.LBB0_1531:
	s_waitcnt vmcnt(5)
	v_lshlrev_b32_e32 v122, 16, v246
	v_and_b32_e32 v123, 0xffff0000, v246
	v_lshlrev_b32_e32 v124, 16, v247
	v_and_b32_e32 v125, 0xffff0000, v247
	v_lshlrev_b32_e32 v126, 16, v248
	v_and_b32_e32 v127, 0xffff0000, v248
	v_lshlrev_b32_e32 v128, 16, v249
	v_and_b32_e32 v129, 0xffff0000, v249
	v_pk_fma_f32 v[120:121], v[120:121], v[56:57], v[124:125]
	v_pk_fma_f32 v[118:119], v[118:119], v[54:55], v[122:123]
	v_pk_fma_f32 v[116:117], v[116:117], v[52:53], v[128:129]
	v_pk_fma_f32 v[114:115], v[114:115], v[50:51], v[126:127]
	s_mov_b64 s[26:27], -1
	s_and_b64 vcc, exec, s[94:95]
	s_cbranch_vccz .LBB0_1534
	v_add_co_u32_e32 v126, vcc, 0x10000, v178
	v_cvt_pk_bf16_f32 v122, v118, v119
	v_cvt_pk_bf16_f32 v123, v120, v121
	v_cvt_pk_bf16_f32 v124, v114, v115
	v_cvt_pk_bf16_f32 v125, v116, v117
	s_nop 1
	v_addc_co_u32_e32 v127, vcc, 0, v179, vcc
	global_store_dwordx4 v[126:127], v[122:125], off offset:256
	s_cbranch_execz .LBB0_1535

.LBB0_1539:
	v_add_co_u32_e32 v208, vcc, 0x30000, v180
	s_mov_b64 s[26:27], -1
	s_waitcnt lgkmcnt(0)
	v_addc_co_u32_e32 v209, vcc, 0, v181, vcc
	global_load_dwordx4 v[242:245], v[208:209], off
	s_nop 0
	global_load_dwordx4 v[246:249], v[208:209], off offset:256
	s_and_b64 vcc, exec, s[94:95]
	s_waitcnt vmcnt(5)
	v_lshlrev_b32_e32 v122, 16, v234
	v_and_b32_e32 v123, 0xffff0000, v234
	v_lshlrev_b32_e32 v118, 16, v235
	v_and_b32_e32 v119, 0xffff0000, v235
	v_lshlrev_b32_e32 v124, 16, v236
	v_and_b32_e32 v125, 0xffff0000, v236
	v_lshlrev_b32_e32 v120, 16, v237
	v_and_b32_e32 v121, 0xffff0000, v237
	v_pk_fma_f32 v[112:113], v[112:113], v[64:65], v[118:119]
	v_pk_fma_f32 v[110:111], v[110:111], v[62:63], v[122:123]
	v_pk_fma_f32 v[108:109], v[108:109], v[60:61], v[120:121]
	v_pk_fma_f32 v[106:107], v[106:107], v[58:59], v[124:125]
	s_cbranch_vccz .LBB0_1541
	v_cvt_pk_bf16_f32 v118, v110, v111
	v_cvt_pk_bf16_f32 v119, v112, v113
	v_cvt_pk_bf16_f32 v120, v106, v107
	v_cvt_pk_bf16_f32 v121, v108, v109
	global_store_dwordx4 v[134:135], v[118:121], off
	s_mov_b64 s[26:27], 0

.LBB0_1545:
	s_waitcnt vmcnt(5)
	v_lshlrev_b32_e32 v106, 16, v238
	v_and_b32_e32 v107, 0xffff0000, v238
	v_lshlrev_b32_e32 v108, 16, v239
	v_and_b32_e32 v109, 0xffff0000, v239
	v_lshlrev_b32_e32 v110, 16, v240
	v_and_b32_e32 v111, 0xffff0000, v240
	v_lshlrev_b32_e32 v112, 16, v241
	v_and_b32_e32 v113, 0xffff0000, v241
	v_pk_fma_f32 v[104:105], v[104:105], v[56:57], v[108:109]
	v_pk_fma_f32 v[102:103], v[102:103], v[54:55], v[106:107]
	v_pk_fma_f32 v[100:101], v[100:101], v[52:53], v[112:113]
	v_pk_fma_f32 v[98:99], v[98:99], v[50:51], v[110:111]
	s_mov_b64 s[26:27], -1
	s_and_b64 vcc, exec, s[94:95]
	s_cbranch_vccz .LBB0_1548
	v_add_co_u32_e32 v110, vcc, 0x20000, v178
	v_cvt_pk_bf16_f32 v106, v102, v103
	v_cvt_pk_bf16_f32 v107, v104, v105
	v_cvt_pk_bf16_f32 v108, v98, v99
	v_cvt_pk_bf16_f32 v109, v100, v101
	s_nop 1
	v_addc_co_u32_e32 v111, vcc, 0, v179, vcc
	global_store_dwordx4 v[110:111], v[106:109], off offset:256
	s_cbranch_execz .LBB0_1549

.LBB0_1553:
	v_add_co_u32_e32 v208, vcc, 0x80000, v180
	s_mov_b64 s[26:27], -1
	s_waitcnt lgkmcnt(0)
	v_addc_co_u32_e32 v209, vcc, 0, v181, vcc
	global_load_dwordx4 v[234:237], v[208:209], off
	s_nop 0
	global_load_dwordx4 v[238:241], v[208:209], off offset:256
	s_and_b64 vcc, exec, s[94:95]
	s_waitcnt vmcnt(5)
	v_lshlrev_b32_e32 v106, 16, v242
	v_and_b32_e32 v107, 0xffff0000, v242
	v_lshlrev_b32_e32 v102, 16, v243
	v_and_b32_e32 v103, 0xffff0000, v243
	v_lshlrev_b32_e32 v108, 16, v244
	v_and_b32_e32 v109, 0xffff0000, v244
	v_lshlrev_b32_e32 v104, 16, v245
	v_and_b32_e32 v105, 0xffff0000, v245
	v_pk_fma_f32 v[96:97], v[96:97], v[64:65], v[102:103]
	v_pk_fma_f32 v[94:95], v[94:95], v[62:63], v[106:107]
	v_pk_fma_f32 v[92:93], v[92:93], v[60:61], v[104:105]
	v_pk_fma_f32 v[90:91], v[90:91], v[58:59], v[108:109]
	s_cbranch_vccz .LBB0_1555
	v_add_co_u32_e32 v106, vcc, 0x30000, v178
	v_cvt_pk_bf16_f32 v102, v94, v95
	v_cvt_pk_bf16_f32 v103, v96, v97
	v_cvt_pk_bf16_f32 v104, v90, v91
	v_cvt_pk_bf16_f32 v105, v92, v93
	s_nop 1
	v_addc_co_u32_e32 v107, vcc, 0, v179, vcc
	global_store_dwordx4 v[106:107], v[102:105], off
	s_mov_b64 s[26:27], 0

.LBB0_1559:
	s_waitcnt vmcnt(5)
	v_lshlrev_b32_e32 v90, 16, v246
	v_and_b32_e32 v91, 0xffff0000, v246
	v_lshlrev_b32_e32 v92, 16, v247
	v_and_b32_e32 v93, 0xffff0000, v247
	v_lshlrev_b32_e32 v94, 16, v248
	v_and_b32_e32 v95, 0xffff0000, v248
	v_lshlrev_b32_e32 v96, 16, v249
	v_and_b32_e32 v97, 0xffff0000, v249
	v_pk_fma_f32 v[88:89], v[88:89], v[56:57], v[92:93]
	v_pk_fma_f32 v[86:87], v[86:87], v[54:55], v[90:91]
	v_pk_fma_f32 v[84:85], v[84:85], v[52:53], v[96:97]
	v_pk_fma_f32 v[82:83], v[82:83], v[50:51], v[94:95]
	s_mov_b64 s[26:27], -1
	s_and_b64 vcc, exec, s[94:95]
	s_cbranch_vccz .LBB0_1562
	v_add_co_u32_e32 v94, vcc, 0x30000, v178
	v_cvt_pk_bf16_f32 v90, v86, v87
	v_cvt_pk_bf16_f32 v91, v88, v89
	v_cvt_pk_bf16_f32 v92, v82, v83
	v_cvt_pk_bf16_f32 v93, v84, v85
	s_nop 1
	v_addc_co_u32_e32 v95, vcc, 0, v179, vcc
	global_store_dwordx4 v[94:95], v[90:93], off offset:256
	s_cbranch_execz .LBB0_1563

.LBB0_1567:
	v_add_co_u32_e32 v208, vcc, 0x90000, v180
	s_mov_b64 s[26:27], -1
	s_waitcnt lgkmcnt(0)
	v_addc_co_u32_e32 v209, vcc, 0, v181, vcc
	global_load_dwordx4 v[242:245], v[208:209], off
	s_nop 0
	global_load_dwordx4 v[246:249], v[208:209], off offset:256
	s_and_b64 vcc, exec, s[94:95]
	s_waitcnt vmcnt(5)
	v_lshlrev_b32_e32 v90, 16, v234
	v_and_b32_e32 v91, 0xffff0000, v234
	v_lshlrev_b32_e32 v86, 16, v235
	v_and_b32_e32 v87, 0xffff0000, v235
	v_lshlrev_b32_e32 v92, 16, v236
	v_and_b32_e32 v93, 0xffff0000, v236
	v_lshlrev_b32_e32 v88, 16, v237
	v_and_b32_e32 v89, 0xffff0000, v237
	v_pk_fma_f32 v[80:81], v[80:81], v[64:65], v[86:87]
	v_pk_fma_f32 v[78:79], v[78:79], v[62:63], v[90:91]
	v_pk_fma_f32 v[76:77], v[76:77], v[60:61], v[88:89]
	v_pk_fma_f32 v[74:75], v[74:75], v[58:59], v[92:93]
	s_cbranch_vccz .LBB0_1569
	v_add_co_u32_e32 v90, vcc, 0x80000, v178
	v_cvt_pk_bf16_f32 v86, v78, v79
	v_cvt_pk_bf16_f32 v87, v80, v81
	v_cvt_pk_bf16_f32 v88, v74, v75
	v_cvt_pk_bf16_f32 v89, v76, v77
	s_nop 1
	v_addc_co_u32_e32 v91, vcc, 0, v179, vcc
	global_store_dwordx4 v[90:91], v[86:89], off
	s_mov_b64 s[26:27], 0

.LBB0_1573:
	s_waitcnt vmcnt(5)
	v_lshlrev_b32_e32 v74, 16, v238
	v_and_b32_e32 v75, 0xffff0000, v238
	v_lshlrev_b32_e32 v76, 16, v239
	v_and_b32_e32 v77, 0xffff0000, v239
	v_lshlrev_b32_e32 v78, 16, v240
	v_and_b32_e32 v79, 0xffff0000, v240
	v_lshlrev_b32_e32 v80, 16, v241
	v_and_b32_e32 v81, 0xffff0000, v241
	v_pk_fma_f32 v[72:73], v[72:73], v[56:57], v[76:77]
	v_pk_fma_f32 v[70:71], v[70:71], v[54:55], v[74:75]
	v_pk_fma_f32 v[68:69], v[68:69], v[52:53], v[80:81]
	v_pk_fma_f32 v[66:67], v[66:67], v[50:51], v[78:79]
	s_mov_b64 s[26:27], -1
	s_and_b64 vcc, exec, s[94:95]
	s_cbranch_vccz .LBB0_1576
	v_add_co_u32_e32 v78, vcc, 0x80000, v178
	v_cvt_pk_bf16_f32 v74, v70, v71
	v_cvt_pk_bf16_f32 v75, v72, v73
	v_cvt_pk_bf16_f32 v76, v66, v67
	v_cvt_pk_bf16_f32 v77, v68, v69
	s_nop 1
	v_addc_co_u32_e32 v79, vcc, 0, v179, vcc
	global_store_dwordx4 v[78:79], v[74:77], off offset:256
	s_cbranch_execz .LBB0_1577

.LBB0_1581:
	v_add_co_u32_e32 v208, vcc, 0xa0000, v180
	s_mov_b64 s[26:27], -1
	s_waitcnt lgkmcnt(0)
	v_addc_co_u32_e32 v209, vcc, 0, v181, vcc
	global_load_dwordx4 v[234:237], v[208:209], off
	s_nop 0
	global_load_dwordx4 v[238:241], v[208:209], off offset:256
	s_and_b64 vcc, exec, s[94:95]
	s_waitcnt vmcnt(5)
	v_lshlrev_b32_e32 v74, 16, v242
	v_and_b32_e32 v75, 0xffff0000, v242
	v_lshlrev_b32_e32 v70, 16, v243
	v_and_b32_e32 v71, 0xffff0000, v243
	v_lshlrev_b32_e32 v76, 16, v244
	v_and_b32_e32 v77, 0xffff0000, v244
	v_lshlrev_b32_e32 v72, 16, v245
	v_and_b32_e32 v73, 0xffff0000, v245
	v_pk_fma_f32 v[48:49], v[48:49], v[64:65], v[70:71]
	v_pk_fma_f32 v[46:47], v[46:47], v[62:63], v[74:75]
	v_pk_fma_f32 v[44:45], v[44:45], v[60:61], v[72:73]
	v_pk_fma_f32 v[42:43], v[42:43], v[58:59], v[76:77]
	s_cbranch_vccz .LBB0_1583
	v_add_co_u32_e32 v74, vcc, 0x90000, v178
	v_cvt_pk_bf16_f32 v70, v46, v47
	v_cvt_pk_bf16_f32 v71, v48, v49
	v_cvt_pk_bf16_f32 v72, v42, v43
	v_cvt_pk_bf16_f32 v73, v44, v45
	s_nop 1
	v_addc_co_u32_e32 v75, vcc, 0, v179, vcc
	global_store_dwordx4 v[74:75], v[70:73], off
	s_mov_b64 s[26:27], 0

.LBB0_1587:
	s_waitcnt vmcnt(5)
	v_lshlrev_b32_e32 v42, 16, v246
	v_and_b32_e32 v43, 0xffff0000, v246
	v_lshlrev_b32_e32 v44, 16, v247
	v_and_b32_e32 v45, 0xffff0000, v247
	v_lshlrev_b32_e32 v46, 16, v248
	v_and_b32_e32 v47, 0xffff0000, v248
	v_lshlrev_b32_e32 v48, 16, v249
	v_and_b32_e32 v49, 0xffff0000, v249
	v_pk_fma_f32 v[40:41], v[40:41], v[56:57], v[44:45]
	v_pk_fma_f32 v[38:39], v[38:39], v[54:55], v[42:43]
	v_pk_fma_f32 v[36:37], v[36:37], v[52:53], v[48:49]
	v_pk_fma_f32 v[34:35], v[34:35], v[50:51], v[46:47]
	s_mov_b64 s[26:27], -1
	s_and_b64 vcc, exec, s[94:95]
	s_cbranch_vccz .LBB0_1590
	v_add_co_u32_e32 v46, vcc, 0x90000, v178
	v_cvt_pk_bf16_f32 v42, v38, v39
	v_cvt_pk_bf16_f32 v43, v40, v41
	v_cvt_pk_bf16_f32 v44, v34, v35
	v_cvt_pk_bf16_f32 v45, v36, v37
	s_nop 1
	v_addc_co_u32_e32 v47, vcc, 0, v179, vcc
	global_store_dwordx4 v[46:47], v[42:45], off offset:256
	s_cbranch_execz .LBB0_1591

.LBB0_1595:
	v_add_co_u32_e32 v208, vcc, 0xb0000, v180
	s_mov_b64 s[26:27], -1
	s_waitcnt lgkmcnt(0)
	v_addc_co_u32_e32 v209, vcc, 0, v181, vcc
	global_load_dwordx4 v[242:245], v[208:209], off
	s_nop 0
	global_load_dwordx4 v[246:249], v[208:209], off offset:256
	s_and_b64 vcc, exec, s[94:95]
	s_waitcnt vmcnt(5)
	v_lshlrev_b32_e32 v42, 16, v234
	v_and_b32_e32 v43, 0xffff0000, v234
	v_lshlrev_b32_e32 v38, 16, v235
	v_and_b32_e32 v39, 0xffff0000, v235
	v_lshlrev_b32_e32 v44, 16, v236
	v_and_b32_e32 v45, 0xffff0000, v236
	v_lshlrev_b32_e32 v40, 16, v237
	v_and_b32_e32 v41, 0xffff0000, v237
	v_pk_fma_f32 v[32:33], v[32:33], v[64:65], v[38:39]
	v_pk_fma_f32 v[30:31], v[30:31], v[62:63], v[42:43]
	v_pk_fma_f32 v[28:29], v[28:29], v[60:61], v[40:41]
	v_pk_fma_f32 v[26:27], v[26:27], v[58:59], v[44:45]
	s_cbranch_vccz .LBB0_1597
	v_add_co_u32_e32 v42, vcc, 0xa0000, v178
	v_cvt_pk_bf16_f32 v38, v30, v31
	v_cvt_pk_bf16_f32 v39, v32, v33
	v_cvt_pk_bf16_f32 v40, v26, v27
	v_cvt_pk_bf16_f32 v41, v28, v29
	s_nop 1
	v_addc_co_u32_e32 v43, vcc, 0, v179, vcc
	global_store_dwordx4 v[42:43], v[38:41], off
	s_mov_b64 s[26:27], 0

.LBB0_1601:
	s_waitcnt vmcnt(5)
	v_lshlrev_b32_e32 v26, 16, v238
	v_and_b32_e32 v27, 0xffff0000, v238
	v_lshlrev_b32_e32 v28, 16, v239
	v_and_b32_e32 v29, 0xffff0000, v239
	v_lshlrev_b32_e32 v30, 16, v240
	v_and_b32_e32 v31, 0xffff0000, v240
	v_lshlrev_b32_e32 v32, 16, v241
	v_and_b32_e32 v33, 0xffff0000, v241
	v_pk_fma_f32 v[24:25], v[24:25], v[56:57], v[28:29]
	v_pk_fma_f32 v[22:23], v[22:23], v[54:55], v[26:27]
	v_pk_fma_f32 v[20:21], v[20:21], v[52:53], v[32:33]
	v_pk_fma_f32 v[18:19], v[18:19], v[50:51], v[30:31]
	s_mov_b64 s[26:27], -1
	s_and_b64 vcc, exec, s[94:95]
	s_cbranch_vccz .LBB0_1604
	v_add_co_u32_e32 v30, vcc, 0xa0000, v178
	v_cvt_pk_bf16_f32 v26, v22, v23
	v_cvt_pk_bf16_f32 v27, v24, v25
	v_cvt_pk_bf16_f32 v28, v18, v19
	v_cvt_pk_bf16_f32 v29, v20, v21
	s_nop 1
	v_addc_co_u32_e32 v31, vcc, 0, v179, vcc
	global_store_dwordx4 v[30:31], v[26:29], off offset:256
	s_cbranch_execz .LBB0_1605

.LBB0_1609:
	s_mov_b64 s[26:27], -1
	s_waitcnt lgkmcnt(0)
	s_and_b64 vcc, exec, s[94:95]
	s_waitcnt vmcnt(3)
	v_lshlrev_b32_e32 v26, 16, v242
	v_and_b32_e32 v27, 0xffff0000, v242
	v_lshlrev_b32_e32 v22, 16, v243
	v_and_b32_e32 v23, 0xffff0000, v243
	v_lshlrev_b32_e32 v28, 16, v244
	v_and_b32_e32 v29, 0xffff0000, v244
	v_lshlrev_b32_e32 v24, 16, v245
	v_and_b32_e32 v25, 0xffff0000, v245
	v_pk_fma_f32 v[16:17], v[16:17], v[64:65], v[22:23]
	v_pk_fma_f32 v[14:15], v[14:15], v[62:63], v[26:27]
	v_pk_fma_f32 v[12:13], v[12:13], v[60:61], v[24:25]
	v_pk_fma_f32 v[10:11], v[10:11], v[58:59], v[28:29]
	s_cbranch_vccz .LBB0_1611
	v_add_co_u32_e32 v26, vcc, 0xb0000, v178
	v_cvt_pk_bf16_f32 v22, v14, v15
	v_cvt_pk_bf16_f32 v23, v16, v17
	v_cvt_pk_bf16_f32 v24, v10, v11
	v_cvt_pk_bf16_f32 v25, v12, v13
	s_nop 1
	v_addc_co_u32_e32 v27, vcc, 0, v179, vcc
	global_store_dwordx4 v[26:27], v[22:25], off
	s_mov_b64 s[26:27], 0

.LBB0_1615:
	s_waitcnt vmcnt(3)
	v_lshlrev_b32_e32 v10, 16, v246
	v_and_b32_e32 v11, 0xffff0000, v246
	v_lshlrev_b32_e32 v12, 16, v247
	v_and_b32_e32 v13, 0xffff0000, v247
	v_lshlrev_b32_e32 v14, 16, v248
	v_and_b32_e32 v15, 0xffff0000, v248
	v_lshlrev_b32_e32 v16, 16, v249
	v_and_b32_e32 v17, 0xffff0000, v249
	v_pk_fma_f32 v[8:9], v[8:9], v[56:57], v[12:13]
	v_pk_fma_f32 v[6:7], v[6:7], v[54:55], v[10:11]
	v_pk_fma_f32 v[4:5], v[4:5], v[52:53], v[16:17]
	v_pk_fma_f32 v[2:3], v[2:3], v[50:51], v[14:15]
	s_mov_b64 s[26:27], -1
	s_and_b64 vcc, exec, s[94:95]
	s_cbranch_vccz .LBB0_1618
	v_add_co_u32_e32 v14, vcc, 0xb0000, v178
	v_cvt_pk_bf16_f32 v10, v6, v7
	v_cvt_pk_bf16_f32 v11, v8, v9
	v_cvt_pk_bf16_f32 v12, v2, v3
	v_cvt_pk_bf16_f32 v13, v4, v5
	s_nop 1
	v_addc_co_u32_e32 v15, vcc, 0, v179, vcc
	global_store_dwordx4 v[14:15], v[10:13], off offset:256
	s_cbranch_execz .LBB0_1619
